# v14 + dropped redundant L1 invalidate in EpiNorm row-stat exchange (slots are read with sc1 loads) + shorter MLA row-max trees (v_max3 chain, exact)
# speedup vs baseline: 1.0096x; 1.0096x over previous
; #define LAS __attribute__((address_space(3)))
; __global__ void __launch_bounds__(NTHR, 2) fwd_megakernel(Params P) {
;     ...
;                 auto kload = [&](LAS const unsigned char* Kl, int kb) {
;                     LAS const unsigned char* kp = Kl + (kb + i) * S96 + g4 * 16;
; #pragma unroll
;                     for (int ks = 0; ks < 3; ++ks) { kf[2 * ks] = *(LAS const bf16x8*)(kp + ks * 64); kf[2 * ks + 1] = *(LAS const bf16x8*)(kp + 16 * S96 + ks * 64); }
;                 };
;                 auto qkm = [&]() {
; #pragma unroll
;                     for (int t = 0; t < 2; ++t) {
;                         s0[t] = __builtin_amdgcn_mfma_f32_16x16x32_bf16(kf[0], qf[t][0], negm[t], 0, 0, 0);
;                         s1[t] = __builtin_amdgcn_mfma_f32_16x16x32_bf16(kf[1], qf[t][0], negm[t], 0, 0, 0);
;                     }
; #pragma unroll
;                     for (int ks = 1; ks < 3; ++ks)
; #pragma unroll
;                         for (int t = 0; t < 2; ++t) {
;                             s0[t] = __builtin_amdgcn_mfma_f32_16x16x32_bf16(kf[2 * ks], qf[t][ks], s0[t], 0, 0, 0);
;                             s1[t] = __builtin_amdgcn_mfma_f32_16x16x32_bf16(kf[2 * ks + 1], qf[t][ks], s1[t], 0, 0, 0);
;                         }
;                 };
;                 auto smpv = [&](LAS const unsigned char* vp) {
;                     bf16x8 pb[2];
; #pragma unroll
;                     for (int t = 0; t < 2; ++t) {
;                         float mx = __builtin_fmaxf(__builtin_fmaxf(s0[t][0], s0[t][1]), s0[t][2]);
;                         mx = __builtin_fmaxf(__builtin_fmaxf(mx, s0[t][3]), s1[t][0]);
;                         mx = __builtin_fmaxf(__builtin_fmaxf(mx, s1[t][1]), s1[t][2]);
;                         mx = __builtin_fmaxf(mx, s1[t][3]);
;                         if (__any(mx > THR)) {
;                             mx = fmaxf(mx, __shfl_xor(mx, 16)); mx = fmaxf(mx, __shfl_xor(mx, 32));
;                             const float dl = fmaxf(mx, 0.f);
;                             const float alpha = __builtin_amdgcn_exp2f(-dl);
;                             negm[t] = negm[t] - dl;
;                             lacc[t] = lacc[t] * alpha;
; #pragma unroll
;                             for (int db = 0; db < 4; ++db) o[t][db] = o[t][db] * alpha;
;                             s0[t] = s0[t] - dl; s1[t] = s1[t] - dl;
;                         }
.LBB0_650:
	s_mul_i32 s22, s36, 0xc000
	s_add_i32 s23, s22, 0
	v_add3_u32 v159, s23, v145, v146
	v_add_u32_e32 v90, s23, v125
	v_add_u32_e32 v148, v90, v124
	ds_read_b128 v[102:105], v148 offset:7168
	ds_read_b128 v[94:97], v148 offset:7232
	ds_read_b128 v[110:113], v148 offset:10752
	ds_read_b128 v[90:93], v148 offset:7296
	ds_read_b128 v[106:109], v148 offset:10816
	ds_read_b128 v[98:101], v148 offset:10880
	ds_read_b64_tr_b16 v[162:163], v159 offset:31232
	ds_read_b64_tr_b16 v[160:161], v159 offset:28672
	ds_read_b64_tr_b16 v[164:165], v159 offset:28704
	ds_read_b64_tr_b16 v[166:167], v159 offset:31264
	ds_read_b64_tr_b16 v[168:169], v159 offset:28736
	ds_read_b64_tr_b16 v[170:171], v159 offset:31296
	ds_read_b64_tr_b16 v[172:173], v159 offset:28768
	ds_read_b64_tr_b16 v[174:175], v159 offset:31328
	v_max3_f32 v114, v192, v193, v194
	v_max3_f32 v114, v114, v195, v196
	v_max3_f32 v114, v114, v197, v198
	v_max_f32_e32 v114, v114, v199
	v_cmp_lt_f32_e32 vcc, s66, v114
	s_cbranch_vccz .LBB0_652
	v_and_b32_e32 v116, 64, v238
	v_xor_b32_e32 v115, 16, v238
	v_add_u32_e32 v116, 64, v116
	v_cmp_lt_i32_e32 vcc, v115, v116
	s_nop 1
	v_cndmask_b32_e32 v115, v238, v115, vcc
	v_lshlrev_b32_e32 v115, 2, v115
	ds_bpermute_b32 v115, v115, v114
	v_max_f32_e32 v114, v114, v114
	s_waitcnt lgkmcnt(0)
	v_max_f32_e32 v115, v115, v115
	v_max_f32_e32 v114, v114, v115
	v_xor_b32_e32 v115, 32, v238
	v_cmp_lt_i32_e32 vcc, v115, v116
	s_nop 1
	v_cndmask_b32_e32 v115, v238, v115, vcc
	v_lshlrev_b32_e32 v115, 2, v115
	ds_bpermute_b32 v115, v115, v114
	s_waitcnt lgkmcnt(0)
	v_max3_f32 v115, v114, v115, 0
	v_exp_f32_e64 v114, -v115
	v_sub_f32_e32 v33, v33, v115
	v_sub_f32_e32 v32, v32, v115
	v_sub_f32_e32 v31, v31, v115
	v_sub_f32_e32 v30, v30, v115
	v_pk_mul_f32 v[72:73], v[72:73], v[114:115] op_sel_hi:[1,0]
	v_pk_mul_f32 v[70:71], v[70:71], v[114:115] op_sel_hi:[1,0]
	v_pk_mul_f32 v[64:65], v[64:65], v[114:115] op_sel_hi:[1,0]
	v_pk_mul_f32 v[62:63], v[62:63], v[114:115] op_sel_hi:[1,0]
	v_pk_mul_f32 v[60:61], v[114:115], v[60:61] op_sel_hi:[0,1]
	v_pk_mul_f32 v[58:59], v[114:115], v[58:59] op_sel_hi:[0,1]
	v_pk_mul_f32 v[48:49], v[114:115], v[48:49] op_sel_hi:[0,1]
	v_pk_mul_f32 v[46:47], v[114:115], v[46:47] op_sel_hi:[0,1]
	v_pk_mul_f32 v[40:41], v[114:115], v[40:41] op_sel_hi:[0,1]
	v_pk_mul_f32 v[38:39], v[114:115], v[38:39] op_sel_hi:[0,1]
	v_sub_f32_e32 v195, v195, v115
	v_sub_f32_e32 v194, v194, v115
	v_sub_f32_e32 v193, v193, v115
	v_sub_f32_e32 v192, v192, v115
	v_sub_f32_e32 v199, v199, v115
	v_sub_f32_e32 v198, v198, v115
	v_sub_f32_e32 v197, v197, v115
	v_sub_f32_e32 v196, v196, v115
.LBB0_652:
	v_max3_f32 v114, v200, v201, v202
	v_max3_f32 v114, v114, v203, v204
	v_max3_f32 v114, v114, v205, v206
	v_max_f32_e32 v114, v114, v207
	v_cmp_lt_f32_e32 vcc, s66, v114
	s_cbranch_vccz .LBB0_654
	v_and_b32_e32 v116, 64, v238
	v_xor_b32_e32 v115, 16, v238
	v_add_u32_e32 v116, 64, v116
	v_cmp_lt_i32_e32 vcc, v115, v116
	s_nop 1
	v_cndmask_b32_e32 v115, v238, v115, vcc
	v_lshlrev_b32_e32 v115, 2, v115
	ds_bpermute_b32 v115, v115, v114
	v_max_f32_e32 v114, v114, v114
	s_waitcnt lgkmcnt(0)
	v_max_f32_e32 v115, v115, v115
	v_max_f32_e32 v114, v114, v115
	v_xor_b32_e32 v115, 32, v238
	v_cmp_lt_i32_e32 vcc, v115, v116
	s_nop 1
	v_cndmask_b32_e32 v115, v238, v115, vcc
	v_lshlrev_b32_e32 v115, 2, v115
	ds_bpermute_b32 v115, v115, v114
	s_waitcnt lgkmcnt(0)
	v_max3_f32 v115, v114, v115, 0
	v_exp_f32_e64 v114, -v115
	v_sub_f32_e32 v29, v29, v115
	v_sub_f32_e32 v28, v28, v115
	v_sub_f32_e32 v27, v27, v115
	v_sub_f32_e32 v26, v26, v115
	v_pk_mul_f32 v[68:69], v[68:69], v[114:115] op_sel_hi:[1,0]
	v_pk_mul_f32 v[66:67], v[66:67], v[114:115] op_sel_hi:[1,0]
	v_pk_mul_f32 v[56:57], v[56:57], v[114:115] op_sel_hi:[1,0]
	v_pk_mul_f32 v[54:55], v[54:55], v[114:115] op_sel_hi:[1,0]
	v_pk_mul_f32 v[52:53], v[114:115], v[52:53] op_sel_hi:[0,1]
	v_pk_mul_f32 v[50:51], v[114:115], v[50:51] op_sel_hi:[0,1]
	v_pk_mul_f32 v[44:45], v[114:115], v[44:45] op_sel_hi:[0,1]
	v_pk_mul_f32 v[42:43], v[114:115], v[42:43] op_sel_hi:[0,1]
	v_pk_mul_f32 v[36:37], v[114:115], v[36:37] op_sel_hi:[0,1]
	v_pk_mul_f32 v[34:35], v[114:115], v[34:35] op_sel_hi:[0,1]
	v_sub_f32_e32 v200, v200, v115
	v_sub_f32_e32 v201, v201, v115
	v_sub_f32_e32 v202, v202, v115
	v_sub_f32_e32 v203, v203, v115
	v_sub_f32_e32 v204, v204, v115
	v_sub_f32_e32 v205, v205, v115
	v_sub_f32_e32 v206, v206, v115
	v_sub_f32_e32 v207, v207, v115
; __global__ void __launch_bounds__(NTHR, 2) fwd_megakernel(Params P) {
;     ...
;                 auto qkm = [&]() {
; #pragma unroll
;                     for (int t = 0; t < 2; ++t) {
;                         s0[t] = __builtin_amdgcn_mfma_f32_16x16x32_bf16(kf[0], qf[t][0], negm[t], 0, 0, 0);
;                         s1[t] = __builtin_amdgcn_mfma_f32_16x16x32_bf16(kf[1], qf[t][0], negm[t], 0, 0, 0);
;                     }
; #pragma unroll
;                     for (int ks = 1; ks < 3; ++ks)
; #pragma unroll
;                         for (int t = 0; t < 2; ++t) {
;                             s0[t] = __builtin_amdgcn_mfma_f32_16x16x32_bf16(kf[2 * ks], qf[t][ks], s0[t], 0, 0, 0);
;                             s1[t] = __builtin_amdgcn_mfma_f32_16x16x32_bf16(kf[2 * ks + 1], qf[t][ks], s1[t], 0, 0, 0);
;                         }
;                 };
;                 auto smpv = [&](LAS const unsigned char* vp) {
;                     bf16x8 pb[2];
; #pragma unroll
;                     for (int t = 0; t < 2; ++t) {
;                         float mx = __builtin_fmaxf(__builtin_fmaxf(s0[t][0], s0[t][1]), s0[t][2]);
;                         mx = __builtin_fmaxf(__builtin_fmaxf(mx, s0[t][3]), s1[t][0]);
;                         mx = __builtin_fmaxf(__builtin_fmaxf(mx, s1[t][1]), s1[t][2]);
;                         mx = __builtin_fmaxf(mx, s1[t][3]);
;                         if (__any(mx > THR)) {
;                             mx = fmaxf(mx, __shfl_xor(mx, 16)); mx = fmaxf(mx, __shfl_xor(mx, 32));
;                             const float dl = fmaxf(mx, 0.f);
;                             const float alpha = __builtin_amdgcn_exp2f(-dl);
;                             negm[t] = negm[t] - dl;
;                             lacc[t] = lacc[t] * alpha;
; #pragma unroll
;                             for (int db = 0; db < 4; ++db) o[t][db] = o[t][db] * alpha;
;                             s0[t] = s0[t] - dl; s1[t] = s1[t] - dl;
;                         }
;                         u32x4 w;
;                         w.x = pk2(__builtin_amdgcn_exp2f(s0[t][0]), __builtin_amdgcn_exp2f(s0[t][1])); w.y = pk2(__builtin_amdgcn_exp2f(s0[t][2]), __builtin_amdgcn_exp2f(s0[t][3]));
;                         w.z = pk2(__builtin_amdgcn_exp2f(s1[t][0]), __builtin_amdgcn_exp2f(s1[t][1])); w.w = pk2(__builtin_amdgcn_exp2f(s1[t][2]), __builtin_amdgcn_exp2f(s1[t][3]));
.LBB0_654:
	s_waitcnt lgkmcnt(8)
	s_nop 1
	v_mfma_f32_16x16x32_bf16 v[208:211], v[102:105], v[8:11], v[30:33]
	v_exp_f32_e32 v78, v200
	v_exp_f32_e32 v79, v201
	v_mfma_f32_16x16x32_bf16 v[212:215], v[110:113], v[8:11], v[30:33]
	v_exp_f32_e32 v74, v204
	v_exp_f32_e32 v75, v205
	v_exp_f32_e32 v86, v192
	v_mfma_f32_16x16x32_bf16 v[216:219], v[102:105], v[14:17], v[26:29]
	v_cvt_pk_bf16_f32 v78, v78, v79
	v_exp_f32_e32 v79, v202
	v_mfma_f32_16x16x32_bf16 v[220:223], v[110:113], v[14:17], v[26:29]
	v_exp_f32_e32 v80, v203
	v_exp_f32_e32 v87, v193
	v_exp_f32_e32 v82, v196
	v_mfma_f32_16x16x32_bf16 v[208:211], v[94:97], v[4:7], v[208:211]
	v_exp_f32_e32 v83, v197
	v_cvt_pk_bf16_f32 v79, v79, v80
	v_mfma_f32_16x16x32_bf16 v[212:215], v[106:109], v[4:7], v[212:215]
	v_cvt_pk_bf16_f32 v80, v74, v75
	v_exp_f32_e32 v74, v206
	v_exp_f32_e32 v75, v207
	v_mfma_f32_16x16x32_bf16 v[216:219], v[94:97], v[18:21], v[216:219]
	v_cvt_pk_bf16_f32 v86, v86, v87
	v_exp_f32_e32 v87, v194
	v_exp_f32_e32 v88, v195
	v_mfma_f32_16x16x32_bf16 v[220:223], v[106:109], v[18:21], v[220:223]
	s_mov_b32 s30, s28
	s_mov_b32 s31, s28
	v_mfma_f32_16x16x32_bf16 v[208:211], v[90:93], v[0:3], v[208:211]
	v_cvt_pk_bf16_f32 v81, v74, v75
	s_mov_b32 s29, s28
	v_mov_b64_e32 v[76:77], s[30:31]
	v_mfma_f32_16x16x32_bf16 v[212:215], v[98:101], v[0:3], v[212:215]
	v_cvt_pk_bf16_f32 v87, v87, v88
	v_cvt_pk_bf16_f32 v88, v82, v83
	v_mfma_f32_16x16x32_bf16 v[216:219], v[90:93], v[22:25], v[216:219]
	v_exp_f32_e32 v82, v198
	v_exp_f32_e32 v83, v199
	v_mov_b64_e32 v[74:75], s[28:29]
	v_mfma_f32_16x16x32_bf16 v[220:223], v[98:101], v[22:25], v[220:223]
	v_add_u32_e32 v114, s23, v145
	v_add_u32_e32 v147, v114, v146
	v_cvt_pk_bf16_f32 v89, v82, v83
	v_mfma_f32_16x16x32_bf16 v[66:69], v[74:77], v[78:81], v[66:69]
	s_nop 0
	v_mfma_f32_16x16x32_bf16 v[70:73], v[74:77], v[86:89], v[70:73]
	s_waitcnt lgkmcnt(2)
	v_mfma_f32_16x16x32_bf16 v[62:65], v[160:163], v[86:89], v[62:65]
	v_mfma_f32_16x16x32_bf16 v[74:77], v[160:163], v[78:81], v[54:57]
	s_waitcnt lgkmcnt(0)
	v_mfma_f32_16x16x32_bf16 v[54:57], v[164:167], v[86:89], v[58:61]
	s_nop 2
	s_waitcnt lgkmcnt(0)
	v_mfma_f32_16x16x32_bf16 v[46:49], v[168:171], v[86:89], v[46:49]
	v_mfma_f32_16x16x32_bf16 v[42:45], v[168:171], v[78:81], v[42:45]
	v_mfma_f32_16x16x32_bf16 v[50:53], v[164:167], v[78:81], v[50:53]
	s_waitcnt lgkmcnt(0)
	v_mfma_f32_16x16x32_bf16 v[38:41], v[172:175], v[86:89], v[38:41]
	v_mfma_f32_16x16x32_bf16 v[34:37], v[172:175], v[78:81], v[34:37]
	ds_read_b128 v[110:113], v148 offset:14336
	s_nop 2
	ds_read_b128 v[102:105], v148 offset:14400
	ds_read_b128 v[118:121], v148 offset:17920
	ds_read_b128 v[98:101], v148 offset:14464
	ds_read_b128 v[114:117], v148 offset:17984
	ds_read_b128 v[106:109], v148 offset:18048
	ds_read_b64_tr_b16 v[178:179], v159 offset:36352
	ds_read_b64_tr_b16 v[176:177], v159 offset:33792
	ds_read_b64_tr_b16 v[180:181], v159 offset:33824
	ds_read_b64_tr_b16 v[182:183], v159 offset:36384
	ds_read_b64_tr_b16 v[184:185], v159 offset:33856
	ds_read_b64_tr_b16 v[186:187], v159 offset:36416
	ds_read_b64_tr_b16 v[188:189], v159 offset:33888
	ds_read_b64_tr_b16 v[190:191], v159 offset:36448
	v_max3_f32 v90, v208, v209, v210
	v_max3_f32 v90, v90, v211, v212
	v_max3_f32 v90, v90, v213, v214
	v_max_f32_e32 v90, v90, v215
	v_cmp_lt_f32_e32 vcc, s66, v90
	s_cbranch_vccz .LBB0_656
	v_and_b32_e32 v92, 64, v238
	v_xor_b32_e32 v91, 16, v238
	v_add_u32_e32 v92, 64, v92
	v_cmp_lt_i32_e32 vcc, v91, v92
	s_nop 1
	v_cndmask_b32_e32 v91, v238, v91, vcc
	v_lshlrev_b32_e32 v91, 2, v91
	ds_bpermute_b32 v91, v91, v90
	v_max_f32_e32 v90, v90, v90
	s_waitcnt lgkmcnt(0)
	v_max_f32_e32 v91, v91, v91
	v_max_f32_e32 v90, v90, v91
	v_xor_b32_e32 v91, 32, v238
	v_cmp_lt_i32_e32 vcc, v91, v92
	s_nop 1
	v_cndmask_b32_e32 v91, v238, v91, vcc
	v_lshlrev_b32_e32 v91, 2, v91
	ds_bpermute_b32 v91, v91, v90
	s_waitcnt lgkmcnt(0)
	v_max3_f32 v91, v90, v91, 0
	v_exp_f32_e64 v90, -v91
	v_sub_f32_e32 v33, v33, v91
	v_sub_f32_e32 v32, v32, v91
	v_sub_f32_e32 v31, v31, v91
	v_sub_f32_e32 v30, v30, v91
	v_pk_mul_f32 v[72:73], v[72:73], v[90:91] op_sel_hi:[1,0]
	v_pk_mul_f32 v[70:71], v[70:71], v[90:91] op_sel_hi:[1,0]
	v_pk_mul_f32 v[64:65], v[64:65], v[90:91] op_sel_hi:[1,0]
	v_pk_mul_f32 v[62:63], v[62:63], v[90:91] op_sel_hi:[1,0]
	v_pk_mul_f32 v[56:57], v[90:91], v[56:57] op_sel_hi:[0,1]
	v_pk_mul_f32 v[54:55], v[90:91], v[54:55] op_sel_hi:[0,1]
	v_pk_mul_f32 v[48:49], v[90:91], v[48:49] op_sel_hi:[0,1]
	v_pk_mul_f32 v[46:47], v[90:91], v[46:47] op_sel_hi:[0,1]
	v_pk_mul_f32 v[40:41], v[90:91], v[40:41] op_sel_hi:[0,1]
	v_pk_mul_f32 v[38:39], v[90:91], v[38:39] op_sel_hi:[0,1]
	v_sub_f32_e32 v211, v211, v91
	v_sub_f32_e32 v210, v210, v91
	v_sub_f32_e32 v209, v209, v91
	v_sub_f32_e32 v208, v208, v91
	v_sub_f32_e32 v215, v215, v91
	v_sub_f32_e32 v214, v214, v91
	v_sub_f32_e32 v213, v213, v91
	v_sub_f32_e32 v212, v212, v91
; __global__ void __launch_bounds__(NTHR, 2) fwd_megakernel(Params P) {
;     ...
;                         float mx = __builtin_fmaxf(__builtin_fmaxf(s0[t][0], s0[t][1]), s0[t][2]);
;                         mx = __builtin_fmaxf(__builtin_fmaxf(mx, s0[t][3]), s1[t][0]);
;                         mx = __builtin_fmaxf(__builtin_fmaxf(mx, s1[t][1]), s1[t][2]);
;                         mx = __builtin_fmaxf(mx, s1[t][3]);
;                         if (__any(mx > THR)) {
;                             mx = fmaxf(mx, __shfl_xor(mx, 16)); mx = fmaxf(mx, __shfl_xor(mx, 32));
;                             const float dl = fmaxf(mx, 0.f);
;                             const float alpha = __builtin_amdgcn_exp2f(-dl);
;                             negm[t] = negm[t] - dl;
;                             lacc[t] = lacc[t] * alpha;
; #pragma unroll
;                             for (int db = 0; db < 4; ++db) o[t][db] = o[t][db] * alpha;
;                             s0[t] = s0[t] - dl; s1[t] = s1[t] - dl;
;                         }
.LBB0_656:
	v_max3_f32 v90, v216, v217, v218
	v_max3_f32 v90, v90, v219, v220
	v_max3_f32 v90, v90, v221, v222
	v_max_f32_e32 v90, v90, v223
	v_cmp_lt_f32_e32 vcc, s66, v90
	s_cbranch_vccz .LBB0_658
	v_and_b32_e32 v92, 64, v238
	v_xor_b32_e32 v91, 16, v238
	v_add_u32_e32 v92, 64, v92
	v_cmp_lt_i32_e32 vcc, v91, v92
	s_nop 1
	v_cndmask_b32_e32 v91, v238, v91, vcc
	v_lshlrev_b32_e32 v91, 2, v91
	ds_bpermute_b32 v91, v91, v90
	v_max_f32_e32 v90, v90, v90
	s_waitcnt lgkmcnt(0)
	v_max_f32_e32 v91, v91, v91
	v_max_f32_e32 v90, v90, v91
	v_xor_b32_e32 v91, 32, v238
	v_cmp_lt_i32_e32 vcc, v91, v92
	s_nop 1
	v_cndmask_b32_e32 v91, v238, v91, vcc
	v_lshlrev_b32_e32 v91, 2, v91
	ds_bpermute_b32 v91, v91, v90
	s_waitcnt lgkmcnt(0)
	v_max3_f32 v91, v90, v91, 0
	v_exp_f32_e64 v90, -v91
	v_sub_f32_e32 v29, v29, v91
	v_sub_f32_e32 v28, v28, v91
	v_sub_f32_e32 v27, v27, v91
	v_sub_f32_e32 v26, v26, v91
	v_pk_mul_f32 v[68:69], v[68:69], v[90:91] op_sel_hi:[1,0]
	v_pk_mul_f32 v[66:67], v[66:67], v[90:91] op_sel_hi:[1,0]
	v_pk_mul_f32 v[76:77], v[76:77], v[90:91] op_sel_hi:[1,0]
	v_pk_mul_f32 v[74:75], v[74:75], v[90:91] op_sel_hi:[1,0]
	v_pk_mul_f32 v[52:53], v[90:91], v[52:53] op_sel_hi:[0,1]
	v_pk_mul_f32 v[50:51], v[90:91], v[50:51] op_sel_hi:[0,1]
	v_pk_mul_f32 v[44:45], v[90:91], v[44:45] op_sel_hi:[0,1]
	v_pk_mul_f32 v[42:43], v[90:91], v[42:43] op_sel_hi:[0,1]
	v_pk_mul_f32 v[36:37], v[90:91], v[36:37] op_sel_hi:[0,1]
	v_pk_mul_f32 v[34:35], v[90:91], v[34:35] op_sel_hi:[0,1]
	v_sub_f32_e32 v216, v216, v91
	v_sub_f32_e32 v217, v217, v91
	v_sub_f32_e32 v218, v218, v91
	v_sub_f32_e32 v219, v219, v91
	v_sub_f32_e32 v220, v220, v91
	v_sub_f32_e32 v221, v221, v91
	v_sub_f32_e32 v222, v222, v91
	v_sub_f32_e32 v223, v223, v91
; __global__ void __launch_bounds__(NTHR, 2) fwd_megakernel(Params P) {
;     ...
;                 auto qkm = [&]() {
; #pragma unroll
;                     for (int t = 0; t < 2; ++t) {
;                         s0[t] = __builtin_amdgcn_mfma_f32_16x16x32_bf16(kf[0], qf[t][0], negm[t], 0, 0, 0);
;                         s1[t] = __builtin_amdgcn_mfma_f32_16x16x32_bf16(kf[1], qf[t][0], negm[t], 0, 0, 0);
;                     }
; #pragma unroll
;                     for (int ks = 1; ks < 3; ++ks)
; #pragma unroll
;                         for (int t = 0; t < 2; ++t) {
;                             s0[t] = __builtin_amdgcn_mfma_f32_16x16x32_bf16(kf[2 * ks], qf[t][ks], s0[t], 0, 0, 0);
;                             s1[t] = __builtin_amdgcn_mfma_f32_16x16x32_bf16(kf[2 * ks + 1], qf[t][ks], s1[t], 0, 0, 0);
;                         }
;                 };
;                 auto smpv = [&](LAS const unsigned char* vp) {
;                     bf16x8 pb[2];
; #pragma unroll
;                     for (int t = 0; t < 2; ++t) {
;                         float mx = __builtin_fmaxf(__builtin_fmaxf(s0[t][0], s0[t][1]), s0[t][2]);
;                         mx = __builtin_fmaxf(__builtin_fmaxf(mx, s0[t][3]), s1[t][0]);
;                         mx = __builtin_fmaxf(__builtin_fmaxf(mx, s1[t][1]), s1[t][2]);
;                         mx = __builtin_fmaxf(mx, s1[t][3]);
;                         if (__any(mx > THR)) {
;                             mx = fmaxf(mx, __shfl_xor(mx, 16)); mx = fmaxf(mx, __shfl_xor(mx, 32));
;                             const float dl = fmaxf(mx, 0.f);
;                             const float alpha = __builtin_amdgcn_exp2f(-dl);
;                             negm[t] = negm[t] - dl;
;                             lacc[t] = lacc[t] * alpha;
; #pragma unroll
;                             for (int db = 0; db < 4; ++db) o[t][db] = o[t][db] * alpha;
;                             s0[t] = s0[t] - dl; s1[t] = s1[t] - dl;
;                         }
;                         u32x4 w;
;                         w.x = pk2(__builtin_amdgcn_exp2f(s0[t][0]), __builtin_amdgcn_exp2f(s0[t][1])); w.y = pk2(__builtin_amdgcn_exp2f(s0[t][2]), __builtin_amdgcn_exp2f(s0[t][3]));
;                         w.z = pk2(__builtin_amdgcn_exp2f(s1[t][0]), __builtin_amdgcn_exp2f(s1[t][1])); w.w = pk2(__builtin_amdgcn_exp2f(s1[t][2]), __builtin_amdgcn_exp2f(s1[t][3]));
.LBB0_658:
	s_waitcnt lgkmcnt(8)
	s_nop 1
	v_mfma_f32_16x16x32_bf16 v[192:195], v[110:113], v[8:11], v[30:33]
	v_exp_f32_e32 v78, v216
	v_exp_f32_e32 v79, v217
	v_mfma_f32_16x16x32_bf16 v[196:199], v[118:121], v[8:11], v[30:33]
	v_exp_f32_e32 v58, v220
	v_exp_f32_e32 v59, v221
	v_mfma_f32_16x16x32_bf16 v[200:203], v[110:113], v[14:17], v[26:29]
	v_exp_f32_e32 v82, v212
	v_cvt_pk_bf16_f32 v154, v78, v79
	v_mfma_f32_16x16x32_bf16 v[204:207], v[118:121], v[14:17], v[26:29]
	v_exp_f32_e32 v78, v218
	v_exp_f32_e32 v79, v219
	v_mfma_f32_16x16x32_bf16 v[192:195], v[102:105], v[4:7], v[192:195]
	v_exp_f32_e32 v83, v213
	s_mov_b32 s30, s28
	v_mfma_f32_16x16x32_bf16 v[196:199], v[114:117], v[4:7], v[196:199]
	s_mov_b32 s31, s28
	v_cvt_pk_bf16_f32 v155, v78, v79
	v_mfma_f32_16x16x32_bf16 v[200:203], v[102:105], v[18:21], v[200:203]
	s_mov_b32 s29, s28
	v_mov_b64_e32 v[80:81], s[30:31]
	v_mfma_f32_16x16x32_bf16 v[204:207], v[114:117], v[18:21], v[204:207]
	v_cvt_pk_bf16_f32 v156, v58, v59
	v_exp_f32_e32 v58, v222
	v_mfma_f32_16x16x32_bf16 v[192:195], v[98:101], v[0:3], v[192:195]
	v_exp_f32_e32 v59, v223
	v_mov_b64_e32 v[78:79], s[28:29]
	v_mfma_f32_16x16x32_bf16 v[196:199], v[106:109], v[0:3], v[196:199]
	v_cvt_pk_bf16_f32 v152, v82, v83
	v_exp_f32_e32 v82, v214
	v_mfma_f32_16x16x32_bf16 v[200:203], v[98:101], v[22:25], v[200:203]
	v_exp_f32_e32 v83, v215
	v_cvt_pk_bf16_f32 v157, v58, v59
	v_mfma_f32_16x16x32_bf16 v[204:207], v[106:109], v[22:25], v[204:207]
	v_exp_f32_e32 v86, v208
	v_exp_f32_e32 v87, v209
	v_cvt_pk_bf16_f32 v153, v82, v83
	v_mfma_f32_16x16x32_bf16 v[94:97], v[78:81], v[154:157], v[66:69]
	s_nop 2
	v_cvt_pk_bf16_f32 v150, v86, v87
	v_exp_f32_e32 v86, v210
	v_exp_f32_e32 v87, v211
	s_waitcnt lgkmcnt(2)
	v_mfma_f32_16x16x32_bf16 v[90:93], v[176:179], v[154:157], v[74:77]
	v_cvt_pk_bf16_f32 v151, v86, v87
	s_nop 1
	v_mfma_f32_16x16x32_bf16 v[58:61], v[78:81], v[150:153], v[70:73]
	s_waitcnt lgkmcnt(0)
	v_mfma_f32_16x16x32_bf16 v[70:73], v[180:183], v[150:153], v[54:57]
	v_mfma_f32_16x16x32_bf16 v[82:85], v[180:183], v[154:157], v[50:53]
	s_nop 2
	s_waitcnt lgkmcnt(0)
	v_mfma_f32_16x16x32_bf16 v[86:89], v[184:187], v[154:157], v[42:45]
	s_nop 2
	v_mfma_f32_16x16x32_bf16 v[78:81], v[176:179], v[150:153], v[62:65]
	v_mfma_f32_16x16x32_bf16 v[66:69], v[184:187], v[150:153], v[46:49]
	s_waitcnt lgkmcnt(0)
	v_mfma_f32_16x16x32_bf16 v[62:65], v[188:191], v[150:153], v[38:41]
	v_mfma_f32_16x16x32_bf16 v[74:77], v[188:191], v[154:157], v[34:37]
	ds_read_b128 v[110:113], v148 offset:21504
	ds_read_b128 v[102:105], v148 offset:21568
	ds_read_b128 v[118:121], v148 offset:25088
	ds_read_b128 v[98:101], v148 offset:21632
	ds_read_b128 v[114:117], v148 offset:25152
	ds_read_b128 v[106:109], v148 offset:25216
	ds_read_b64_tr_b16 v[162:163], v159 offset:41472
	ds_read_b64_tr_b16 v[160:161], v159 offset:38912
	ds_read_b64_tr_b16 v[164:165], v159 offset:38944
	ds_read_b64_tr_b16 v[166:167], v159 offset:41504
	ds_read_b64_tr_b16 v[168:169], v159 offset:38976
	ds_read_b64_tr_b16 v[170:171], v159 offset:41536
	ds_read_b64_tr_b16 v[172:173], v159 offset:39008
	ds_read_b64_tr_b16 v[174:175], v159 offset:41568
	v_max3_f32 v50, v192, v193, v194
	v_max3_f32 v50, v50, v195, v196
	v_max3_f32 v50, v50, v197, v198
	v_max_f32_e32 v50, v50, v199
	v_cmp_lt_f32_e32 vcc, s66, v50
	s_cbranch_vccz .LBB0_660
	v_and_b32_e32 v52, 64, v238
	v_xor_b32_e32 v51, 16, v238
	v_add_u32_e32 v52, 64, v52
	v_cmp_lt_i32_e32 vcc, v51, v52
	s_nop 1
	v_cndmask_b32_e32 v51, v238, v51, vcc
	v_lshlrev_b32_e32 v51, 2, v51
	ds_bpermute_b32 v51, v51, v50
	v_max_f32_e32 v50, v50, v50
	s_waitcnt lgkmcnt(0)
	v_max_f32_e32 v51, v51, v51
	v_max_f32_e32 v50, v50, v51
	v_xor_b32_e32 v51, 32, v238
	v_cmp_lt_i32_e32 vcc, v51, v52
	s_nop 1
	v_cndmask_b32_e32 v51, v238, v51, vcc
	v_lshlrev_b32_e32 v51, 2, v51
	ds_bpermute_b32 v51, v51, v50
	s_waitcnt lgkmcnt(0)
	v_max3_f32 v51, v50, v51, 0
	v_exp_f32_e64 v50, -v51
	v_sub_f32_e32 v33, v33, v51
	v_sub_f32_e32 v32, v32, v51
	v_sub_f32_e32 v31, v31, v51
	v_sub_f32_e32 v30, v30, v51
	v_pk_mul_f32 v[60:61], v[60:61], v[50:51] op_sel_hi:[1,0]
	v_pk_mul_f32 v[58:59], v[58:59], v[50:51] op_sel_hi:[1,0]
	v_pk_mul_f32 v[80:81], v[80:81], v[50:51] op_sel_hi:[1,0]
	v_pk_mul_f32 v[78:79], v[78:79], v[50:51] op_sel_hi:[1,0]
	v_pk_mul_f32 v[72:73], v[50:51], v[72:73] op_sel_hi:[0,1]
	v_pk_mul_f32 v[70:71], v[50:51], v[70:71] op_sel_hi:[0,1]
	v_pk_mul_f32 v[68:69], v[50:51], v[68:69] op_sel_hi:[0,1]
	v_pk_mul_f32 v[66:67], v[50:51], v[66:67] op_sel_hi:[0,1]
	v_pk_mul_f32 v[64:65], v[50:51], v[64:65] op_sel_hi:[0,1]
	v_pk_mul_f32 v[62:63], v[50:51], v[62:63] op_sel_hi:[0,1]
	v_sub_f32_e32 v195, v195, v51
	v_sub_f32_e32 v194, v194, v51
	v_sub_f32_e32 v193, v193, v51
	v_sub_f32_e32 v192, v192, v51
	v_sub_f32_e32 v199, v199, v51
	v_sub_f32_e32 v198, v198, v51
	v_sub_f32_e32 v197, v197, v51
	v_sub_f32_e32 v196, v196, v51
.LBB0_660:
	v_max3_f32 v50, v200, v201, v202
	v_max3_f32 v50, v50, v203, v204
	v_max3_f32 v50, v50, v205, v206
	v_max_f32_e32 v50, v50, v207
	v_cmp_lt_f32_e32 vcc, s66, v50
	s_cbranch_vccz .LBB0_662
	v_and_b32_e32 v52, 64, v238
	v_xor_b32_e32 v51, 16, v238
	v_add_u32_e32 v52, 64, v52
	v_cmp_lt_i32_e32 vcc, v51, v52
	s_nop 1
	v_cndmask_b32_e32 v51, v238, v51, vcc
	v_lshlrev_b32_e32 v51, 2, v51
	ds_bpermute_b32 v51, v51, v50
	v_max_f32_e32 v50, v50, v50
	s_waitcnt lgkmcnt(0)
	v_max_f32_e32 v51, v51, v51
	v_max_f32_e32 v50, v50, v51
	v_xor_b32_e32 v51, 32, v238
	v_cmp_lt_i32_e32 vcc, v51, v52
	s_nop 1
	v_cndmask_b32_e32 v51, v238, v51, vcc
	v_lshlrev_b32_e32 v51, 2, v51
	ds_bpermute_b32 v51, v51, v50
	s_waitcnt lgkmcnt(0)
	v_max3_f32 v51, v50, v51, 0
	v_exp_f32_e64 v50, -v51
	v_sub_f32_e32 v29, v29, v51
	v_sub_f32_e32 v28, v28, v51
	v_sub_f32_e32 v27, v27, v51
	v_sub_f32_e32 v26, v26, v51
	v_pk_mul_f32 v[96:97], v[96:97], v[50:51] op_sel_hi:[1,0]
	v_pk_mul_f32 v[94:95], v[94:95], v[50:51] op_sel_hi:[1,0]
	v_pk_mul_f32 v[92:93], v[92:93], v[50:51] op_sel_hi:[1,0]
	v_pk_mul_f32 v[90:91], v[90:91], v[50:51] op_sel_hi:[1,0]
	v_pk_mul_f32 v[84:85], v[50:51], v[84:85] op_sel_hi:[0,1]
	v_pk_mul_f32 v[82:83], v[50:51], v[82:83] op_sel_hi:[0,1]
	v_pk_mul_f32 v[88:89], v[50:51], v[88:89] op_sel_hi:[0,1]
	v_pk_mul_f32 v[86:87], v[50:51], v[86:87] op_sel_hi:[0,1]
	v_pk_mul_f32 v[76:77], v[50:51], v[76:77] op_sel_hi:[0,1]
	v_pk_mul_f32 v[74:75], v[50:51], v[74:75] op_sel_hi:[0,1]
	v_sub_f32_e32 v200, v200, v51
	v_sub_f32_e32 v201, v201, v51
	v_sub_f32_e32 v202, v202, v51
	v_sub_f32_e32 v203, v203, v51
	v_sub_f32_e32 v204, v204, v51
	v_sub_f32_e32 v205, v205, v51
	v_sub_f32_e32 v206, v206, v51
	v_sub_f32_e32 v207, v207, v51

; #define LAS __attribute__((address_space(3)))
; #define MLA_STEP(KLN, KBN, VL, KBV) do { kload(KLN, KBN); __builtin_amdgcn_sched_barrier(0); smpv(MLA_VP(VL, KBV)); qkm(); __builtin_amdgcn_sched_barrier(0); } while (0)
; __global__ void __launch_bounds__(NTHR, 2) fwd_megakernel(Params P) {
;     ...
;                 auto smpv = [&](LAS const unsigned char* vp) {
;                     bf16x8 pb[2];
; #pragma unroll
;                     for (int t = 0; t < 2; ++t) {
;                         float mx = __builtin_fmaxf(__builtin_fmaxf(s0[t][0], s0[t][1]), s0[t][2]);
;                         mx = __builtin_fmaxf(__builtin_fmaxf(mx, s0[t][3]), s1[t][0]);
;                         mx = __builtin_fmaxf(__builtin_fmaxf(mx, s1[t][1]), s1[t][2]);
;                         mx = __builtin_fmaxf(mx, s1[t][3]);
;                         if (__any(mx > THR)) {
;                             mx = fmaxf(mx, __shfl_xor(mx, 16)); mx = fmaxf(mx, __shfl_xor(mx, 32));
;                             const float dl = fmaxf(mx, 0.f);
;                             const float alpha = __builtin_amdgcn_exp2f(-dl);
;                             negm[t] = negm[t] - dl;
;                             lacc[t] = lacc[t] * alpha;
; #pragma unroll
;                             for (int db = 0; db < 4; ++db) o[t][db] = o[t][db] * alpha;
;                             s0[t] = s0[t] - dl; s1[t] = s1[t] - dl;
;                         }
;     ...
;                     const int bn = (bc == 2) ? 0 : bc + 1, bp = (bc == 0) ? 2 : bc - 1;
;                     LAS const unsigned char* Kl = lds + bc * BUF_BYTES; LAS const unsigned char* Vl = Kl + KB_BYTES;
;                     MLA_STEP(Kl, 32, Vl, 0);
;                     MLA_STEP(Kl, 64, Vl, 32);
;                     MLA_STEP(Kl, 96, Vl, 64);
;                     asm volatile("s_waitcnt vmcnt(0)" ::: "memory");
;                     __syncthreads();
;                     if (c + 2 < 32) dma(c + 2, bp);
;                     if (c + 1 < 32) { MLA_STEP(lds + bn * BUF_BYTES, 0, Vl, 96); }
.LBB0_664:
	s_add_i32 s22, s36, 1
	s_cmp_lg_u32 s36, 2
	s_cselect_b32 s36, s22, 0
	s_mul_i32 s22, s36, 0xc000
	v_add_u32_e32 v90, s22, v144
	ds_read_b128 v[98:101], v90
	ds_read_b128 v[86:89], v90 offset:64
	ds_read_b128 v[106:109], v90 offset:3584
	ds_read_b128 v[94:97], v90 offset:128
	ds_read_b128 v[102:105], v90 offset:3648
	ds_read_b128 v[90:93], v90 offset:3712
	ds_read_b64_tr_b16 v[178:179], v159 offset:46592
	ds_read_b64_tr_b16 v[176:177], v159 offset:44032
	ds_read_b64_tr_b16 v[180:181], v159 offset:44064
	ds_read_b64_tr_b16 v[182:183], v159 offset:46624
	ds_read_b64_tr_b16 v[184:185], v159 offset:44096
	ds_read_b64_tr_b16 v[186:187], v159 offset:46656
	ds_read_b64_tr_b16 v[188:189], v159 offset:44128
	ds_read_b64_tr_b16 v[190:191], v159 offset:46688
	v_max3_f32 v114, v208, v209, v210
	v_max3_f32 v114, v114, v211, v212
	v_max3_f32 v114, v114, v213, v214
	v_max_f32_e32 v114, v114, v215
	v_cmp_lt_f32_e32 vcc, s66, v114
	s_cbranch_vccz .LBB0_666
	v_and_b32_e32 v116, 64, v238
	v_xor_b32_e32 v115, 16, v238
	v_add_u32_e32 v116, 64, v116
	v_cmp_lt_i32_e32 vcc, v115, v116
	s_nop 1
	v_cndmask_b32_e32 v115, v238, v115, vcc
	v_lshlrev_b32_e32 v115, 2, v115
	ds_bpermute_b32 v115, v115, v114
	v_max_f32_e32 v114, v114, v114
	s_waitcnt lgkmcnt(0)
	v_max_f32_e32 v115, v115, v115
	v_max_f32_e32 v114, v114, v115
	v_xor_b32_e32 v115, 32, v238
	v_cmp_lt_i32_e32 vcc, v115, v116
	s_nop 1
	v_cndmask_b32_e32 v115, v238, v115, vcc
	v_lshlrev_b32_e32 v115, 2, v115
	ds_bpermute_b32 v115, v115, v114
	s_waitcnt lgkmcnt(0)
	v_max3_f32 v115, v114, v115, 0
	v_exp_f32_e64 v114, -v115
	v_sub_f32_e32 v33, v33, v115
	v_sub_f32_e32 v32, v32, v115
	v_sub_f32_e32 v31, v31, v115
	v_sub_f32_e32 v30, v30, v115
	v_pk_mul_f32 v[52:53], v[52:53], v[114:115] op_sel_hi:[1,0]
	v_pk_mul_f32 v[50:51], v[50:51], v[114:115] op_sel_hi:[1,0]
	v_pk_mul_f32 v[48:49], v[48:49], v[114:115] op_sel_hi:[1,0]
	v_pk_mul_f32 v[46:47], v[46:47], v[114:115] op_sel_hi:[1,0]
	v_pk_mul_f32 v[44:45], v[114:115], v[44:45] op_sel_hi:[0,1]
	v_pk_mul_f32 v[42:43], v[114:115], v[42:43] op_sel_hi:[0,1]
	v_pk_mul_f32 v[40:41], v[114:115], v[40:41] op_sel_hi:[0,1]
	v_pk_mul_f32 v[38:39], v[114:115], v[38:39] op_sel_hi:[0,1]
	v_pk_mul_f32 v[36:37], v[114:115], v[36:37] op_sel_hi:[0,1]
	v_pk_mul_f32 v[34:35], v[114:115], v[34:35] op_sel_hi:[0,1]
	v_sub_f32_e32 v211, v211, v115
	v_sub_f32_e32 v210, v210, v115
	v_sub_f32_e32 v209, v209, v115
	v_sub_f32_e32 v208, v208, v115
	v_sub_f32_e32 v215, v215, v115
	v_sub_f32_e32 v214, v214, v115
	v_sub_f32_e32 v213, v213, v115
	v_sub_f32_e32 v212, v212, v115
.LBB0_666:
	v_max3_f32 v114, v216, v217, v218
	v_max3_f32 v114, v114, v219, v220
	v_max3_f32 v114, v114, v221, v222
	v_max_f32_e32 v114, v114, v223
	v_cmp_lt_f32_e32 vcc, s66, v114
	s_cbranch_vccz .LBB0_649
	v_and_b32_e32 v116, 64, v238
	v_xor_b32_e32 v115, 16, v238
	v_add_u32_e32 v116, 64, v116
	v_cmp_lt_i32_e32 vcc, v115, v116
	s_nop 1
	v_cndmask_b32_e32 v115, v238, v115, vcc
	v_lshlrev_b32_e32 v115, 2, v115
	ds_bpermute_b32 v115, v115, v114
	v_max_f32_e32 v114, v114, v114
	s_waitcnt lgkmcnt(0)
	v_max_f32_e32 v115, v115, v115
	v_max_f32_e32 v114, v114, v115
	v_xor_b32_e32 v115, 32, v238
	v_cmp_lt_i32_e32 vcc, v115, v116
	s_nop 1
	v_cndmask_b32_e32 v115, v238, v115, vcc
	v_lshlrev_b32_e32 v115, 2, v115
	ds_bpermute_b32 v115, v115, v114
	s_waitcnt lgkmcnt(0)
	v_max3_f32 v115, v114, v115, 0
	v_exp_f32_e64 v114, -v115
	v_sub_f32_e32 v29, v29, v115
	v_sub_f32_e32 v28, v28, v115
	v_sub_f32_e32 v27, v27, v115
	v_sub_f32_e32 v26, v26, v115
	v_pk_mul_f32 v[60:61], v[60:61], v[114:115] op_sel_hi:[1,0]
	v_pk_mul_f32 v[58:59], v[58:59], v[114:115] op_sel_hi:[1,0]
	v_pk_mul_f32 v[56:57], v[56:57], v[114:115] op_sel_hi:[1,0]
	v_pk_mul_f32 v[54:55], v[54:55], v[114:115] op_sel_hi:[1,0]
	v_pk_mul_f32 v[84:85], v[114:115], v[84:85] op_sel_hi:[0,1]
	v_pk_mul_f32 v[82:83], v[114:115], v[82:83] op_sel_hi:[0,1]
	v_pk_mul_f32 v[80:81], v[114:115], v[80:81] op_sel_hi:[0,1]
	v_pk_mul_f32 v[78:79], v[114:115], v[78:79] op_sel_hi:[0,1]
	v_pk_mul_f32 v[76:77], v[114:115], v[76:77] op_sel_hi:[0,1]
	v_pk_mul_f32 v[74:75], v[114:115], v[74:75] op_sel_hi:[0,1]
	v_sub_f32_e32 v216, v216, v115
	v_sub_f32_e32 v217, v217, v115
	v_sub_f32_e32 v218, v218, v115
	v_sub_f32_e32 v219, v219, v115
	v_sub_f32_e32 v220, v220, v115
	v_sub_f32_e32 v221, v221, v115
	v_sub_f32_e32 v222, v222, v115
	v_sub_f32_e32 v223, v223, v115
	s_branch .LBB0_649

;     __device__ __forceinline__ void rowstat(const f32x4 (&v)[2][2][4][2], const Unit& u, int wr, int wc, int fr, int fq, float* slot, unsigned* cnt) const {
;     ...
;         if (wid == 0) {
;             unsigned sp = 0;
;             while ((unsigned)__builtin_amdgcn_readfirstlane(__hip_atomic_load(cnt + 64 * u.pm, __ATOMIC_RELAXED, __HIP_MEMORY_SCOPE_AGENT)) < 16u) { __builtin_amdgcn_s_sleep(2); if (++sp > (1u << 20)) break; }
;             __builtin_amdgcn_fence(__ATOMIC_ACQUIRE, "agent");
;         }
;         asm volatile("s_waitcnt vmcnt(0) lgkmcnt(0)" ::: "memory"); __builtin_amdgcn_s_barrier(); asm volatile("" ::: "memory");
;         if (tid < 256) {
;             const float* sp4 = slot + ((size_t)u.pm * BM + tid) * 4;
;             const float t0 = __hip_atomic_load(sp4 + 0, __ATOMIC_RELAXED, __HIP_MEMORY_SCOPE_AGENT), t1 = __hip_atomic_load(sp4 + 1, __ATOMIC_RELAXED, __HIP_MEMORY_SCOPE_AGENT);
;             const float t2 = __hip_atomic_load(sp4 + 2, __ATOMIC_RELAXED, __HIP_MEMORY_SCOPE_AGENT), t3 = __hip_atomic_load(sp4 + 3, __ATOMIC_RELAXED, __HIP_MEMORY_SCOPE_AGENT);
;             S[tid] = rsqrtf(((t0 + t1) + (t2 + t3)) * (1.0f / DM) + EPS);
;         }
.LBB0_945:
	s_waitcnt lgkmcnt(0)
.LBB0_946:
	s_waitcnt vmcnt(0) lgkmcnt(0)
	s_barrier
	s_and_saveexec_b64 s[40:41], s[4:5]
	s_cbranch_execz .LBB0_948
	s_ashr_i32 s83, s82, 31
	s_lshl_b64 s[42:43], s[82:83], 12
	s_waitcnt lgkmcnt(0)
	v_lshl_add_u64 v[130:131], v[144:145], 0, s[42:43]
	global_load_dword v132, v[130:131], off sc1
	global_load_dword v134, v[130:131], off offset:4 sc1
	global_load_dword v133, v[130:131], off offset:8 sc1
	global_load_dword v135, v[130:131], off offset:12 sc1
	s_mov_b32 s15, 0x800000
	s_waitcnt vmcnt(0)
	v_pk_add_f32 v[130:131], v[132:133], v[134:135]
	s_nop 0
	v_add_f32_e32 v130, v130, v131
	v_fmamk_f32 v130, v130, 0x3a800000, v237
	v_mul_f32_e32 v131, 0x4b800000, v130
	v_cmp_gt_f32_e32 vcc, s15, v130
	s_nop 1
	v_cndmask_b32_e32 v130, v130, v131, vcc
	v_rsq_f32_e32 v130, v130
	s_nop 0
	v_mul_f32_e32 v131, 0x45800000, v130
	v_cndmask_b32_e32 v130, v130, v131, vcc
	ds_write_b32 v233, v130

;     __device__ __forceinline__ void rowstat(const f32x4 (&v)[2][2][4][2], const Unit& u, int wr, int wc, int fr, int fq, float* slot, unsigned* cnt) const {
;     ...
;         if (wid == 0) {
;             unsigned sp = 0;
;             while ((unsigned)__builtin_amdgcn_readfirstlane(__hip_atomic_load(cnt + 64 * u.pm, __ATOMIC_RELAXED, __HIP_MEMORY_SCOPE_AGENT)) < 16u) { __builtin_amdgcn_s_sleep(2); if (++sp > (1u << 20)) break; }
;             __builtin_amdgcn_fence(__ATOMIC_ACQUIRE, "agent");
;         }
;         asm volatile("s_waitcnt vmcnt(0) lgkmcnt(0)" ::: "memory"); __builtin_amdgcn_s_barrier(); asm volatile("" ::: "memory");
;         if (tid < 256) {
;             const float* sp4 = slot + ((size_t)u.pm * BM + tid) * 4;
;             const float t0 = __hip_atomic_load(sp4 + 0, __ATOMIC_RELAXED, __HIP_MEMORY_SCOPE_AGENT), t1 = __hip_atomic_load(sp4 + 1, __ATOMIC_RELAXED, __HIP_MEMORY_SCOPE_AGENT);
;             const float t2 = __hip_atomic_load(sp4 + 2, __ATOMIC_RELAXED, __HIP_MEMORY_SCOPE_AGENT), t3 = __hip_atomic_load(sp4 + 3, __ATOMIC_RELAXED, __HIP_MEMORY_SCOPE_AGENT);
;             S[tid] = rsqrtf(((t0 + t1) + (t2 + t3)) * (1.0f / DM) + EPS);
;         }
.LBB0_975:
	s_waitcnt lgkmcnt(0)
.LBB0_976:
	s_waitcnt vmcnt(0) lgkmcnt(0)
	s_barrier
	s_and_saveexec_b64 s[8:9], s[4:5]
	s_cbranch_execz .LBB0_978
	s_ashr_i32 s83, s82, 31
	s_lshl_b64 s[40:41], s[82:83], 12
	s_waitcnt lgkmcnt(0)
	v_lshl_add_u64 v[26:27], v[146:147], 0, s[40:41]
	global_load_dword v28, v[26:27], off sc1
	global_load_dword v30, v[26:27], off offset:4 sc1
	global_load_dword v29, v[26:27], off offset:8 sc1
	global_load_dword v31, v[26:27], off offset:12 sc1
	s_mov_b32 s15, 0x800000
	s_waitcnt vmcnt(0)
	v_pk_add_f32 v[26:27], v[28:29], v[30:31]
	s_nop 0
	v_add_f32_e32 v26, v26, v27
	v_fmamk_f32 v26, v26, 0x3a800000, v237
	v_mul_f32_e32 v27, 0x4b800000, v26
	v_cmp_gt_f32_e32 vcc, s15, v26
	s_nop 1
	v_cndmask_b32_e32 v26, v26, v27, vcc
	v_rsq_f32_e32 v26, v26
	s_nop 0
	v_mul_f32_e32 v27, 0x45800000, v26
	v_cndmask_b32_e32 v26, v26, v27, vcc
	ds_write_b32 v233, v26

;     __device__ __forceinline__ void rowstat(const f32x4 (&v)[2][2][4][2], const Unit& u, int wr, int wc, int fr, int fq, float* slot, unsigned* cnt) const {
;     ...
;         if (wid == 0) {
;             unsigned sp = 0;
;             while ((unsigned)__builtin_amdgcn_readfirstlane(__hip_atomic_load(cnt + 64 * u.pm, __ATOMIC_RELAXED, __HIP_MEMORY_SCOPE_AGENT)) < 16u) { __builtin_amdgcn_s_sleep(2); if (++sp > (1u << 20)) break; }
;             __builtin_amdgcn_fence(__ATOMIC_ACQUIRE, "agent");
;         }
;         asm volatile("s_waitcnt vmcnt(0) lgkmcnt(0)" ::: "memory"); __builtin_amdgcn_s_barrier(); asm volatile("" ::: "memory");
;         if (tid < 256) {
;             const float* sp4 = slot + ((size_t)u.pm * BM + tid) * 4;
;             const float t0 = __hip_atomic_load(sp4 + 0, __ATOMIC_RELAXED, __HIP_MEMORY_SCOPE_AGENT), t1 = __hip_atomic_load(sp4 + 1, __ATOMIC_RELAXED, __HIP_MEMORY_SCOPE_AGENT);
;             const float t2 = __hip_atomic_load(sp4 + 2, __ATOMIC_RELAXED, __HIP_MEMORY_SCOPE_AGENT), t3 = __hip_atomic_load(sp4 + 3, __ATOMIC_RELAXED, __HIP_MEMORY_SCOPE_AGENT);
;             S[tid] = rsqrtf(((t0 + t1) + (t2 + t3)) * (1.0f / DM) + EPS);
;         }
.LBB0_1217:
	s_waitcnt lgkmcnt(0)
.LBB0_1218:
	s_waitcnt vmcnt(0) lgkmcnt(0)
	s_barrier
	s_and_saveexec_b64 s[8:9], s[2:3]
	s_cbranch_execz .LBB0_1220
	s_ashr_i32 s97, s96, 31
	s_lshl_b64 s[50:51], s[96:97], 12
	s_waitcnt lgkmcnt(0)
	v_lshl_add_u64 v[130:131], v[156:157], 0, s[50:51]
	global_load_dword v132, v[130:131], off sc1
	global_load_dword v134, v[130:131], off offset:4 sc1
	global_load_dword v133, v[130:131], off offset:8 sc1
	global_load_dword v135, v[130:131], off offset:12 sc1
	s_mov_b32 s49, 0x800000
	s_waitcnt vmcnt(0)
	v_pk_add_f32 v[130:131], v[132:133], v[134:135]
	s_nop 0
	v_add_f32_e32 v130, v130, v131
	v_fmamk_f32 v130, v130, 0x3a800000, v237
	v_mul_f32_e32 v131, 0x4b800000, v130
	v_cmp_gt_f32_e32 vcc, s49, v130
	s_nop 1
	v_cndmask_b32_e32 v130, v130, v131, vcc
	v_rsq_f32_e32 v130, v130
	s_nop 0
	v_mul_f32_e32 v131, 0x45800000, v130
	v_cndmask_b32_e32 v130, v130, v131, vcc
	ds_write_b32 v245, v130

;     __device__ __forceinline__ void rowstat(const f32x4 (&v)[2][2][4][2], const Unit& u, int wr, int wc, int fr, int fq, float* slot, unsigned* cnt) const {
;     ...
;         if (wid == 0) {
;             unsigned sp = 0;
;             while ((unsigned)__builtin_amdgcn_readfirstlane(__hip_atomic_load(cnt + 64 * u.pm, __ATOMIC_RELAXED, __HIP_MEMORY_SCOPE_AGENT)) < 16u) { __builtin_amdgcn_s_sleep(2); if (++sp > (1u << 20)) break; }
;             __builtin_amdgcn_fence(__ATOMIC_ACQUIRE, "agent");
;         }
;         asm volatile("s_waitcnt vmcnt(0) lgkmcnt(0)" ::: "memory"); __builtin_amdgcn_s_barrier(); asm volatile("" ::: "memory");
;         if (tid < 256) {
;             const float* sp4 = slot + ((size_t)u.pm * BM + tid) * 4;
;             const float t0 = __hip_atomic_load(sp4 + 0, __ATOMIC_RELAXED, __HIP_MEMORY_SCOPE_AGENT), t1 = __hip_atomic_load(sp4 + 1, __ATOMIC_RELAXED, __HIP_MEMORY_SCOPE_AGENT);
;             const float t2 = __hip_atomic_load(sp4 + 2, __ATOMIC_RELAXED, __HIP_MEMORY_SCOPE_AGENT), t3 = __hip_atomic_load(sp4 + 3, __ATOMIC_RELAXED, __HIP_MEMORY_SCOPE_AGENT);
;             S[tid] = rsqrtf(((t0 + t1) + (t2 + t3)) * (1.0f / DM) + EPS);
;         }
.LBB0_1247:
	s_waitcnt lgkmcnt(0)
.LBB0_1248:
	s_waitcnt vmcnt(0) lgkmcnt(0)
	s_barrier
	s_and_saveexec_b64 s[6:7], s[2:3]
	s_cbranch_execz .LBB0_1250
	s_ashr_i32 s97, s96, 31
	s_lshl_b64 s[8:9], s[96:97], 12
	s_waitcnt lgkmcnt(0)
	v_lshl_add_u64 v[26:27], v[158:159], 0, s[8:9]
	global_load_dword v28, v[26:27], off sc1
	global_load_dword v30, v[26:27], off offset:4 sc1
	global_load_dword v29, v[26:27], off offset:8 sc1
	global_load_dword v31, v[26:27], off offset:12 sc1
	s_mov_b32 s8, 0x800000
	s_waitcnt vmcnt(0)
	v_pk_add_f32 v[26:27], v[28:29], v[30:31]
	s_nop 0
	v_add_f32_e32 v26, v26, v27
	v_fmamk_f32 v26, v26, 0x3a800000, v237
	v_mul_f32_e32 v27, 0x4b800000, v26
	v_cmp_gt_f32_e32 vcc, s8, v26
	s_nop 1
	v_cndmask_b32_e32 v26, v26, v27, vcc
	v_rsq_f32_e32 v26, v26
	s_nop 0
	v_mul_f32_e32 v27, 0x45800000, v26
	v_cndmask_b32_e32 v26, v26, v27, vcc
	ds_write_b32 v245, v26
